# GEMM1 mainloop rewritten by hand: A/B K-slabs staged by LDS-DMA (global_load_lds_dwordx4, source-side XOR swizzle) instead of VGPR + ds_write_b128; DMA issue interleaved under LDS latency/MFMAs; next
# speedup vs baseline: 1.0306x; 1.0211x over previous
; template <class AL>
; DI void gemm_mainloop(f32x16 (&acc)[2][2], GemmRegs<AL>& G, bool pre, const AL& al, const u16* __restrict__ Bt, int ldb, int n0, int nk, char* sm,
;                       bool has_next, const AL& aln, int n0n) {
;     const int t = opaque(threadIdx.x), lane = t & 63, w = t >> 6;
;     const int wm = w >> 1, wn = w & 1, r = lane & 31, h = lane >> 5;
;     const int lrow = t >> 3, lch = t & 7;
;     typename AL::Raw& RA0 = G.RA0; typename AL::Raw& RA1 = G.RA1;
;     bf16x8 (&RB0)[4] = G.RB0; bf16x8 (&RB1)[4] = G.RB1;
;     const u16* bp = Bt + (size_t)(n0 + lrow) * ldb + lch * 8;
;     const u16* bpn = Bt + (size_t)(n0n + lrow) * ldb + lch * 8;
;     auto loadB = [&](bf16x8 (&rb)[4], int kt) {
; #pragma unroll
;         for (int i = 0; i < 4; ++i) rb[i] = *(const bf16x8*)(bp + (size_t)(32 * i) * ldb + kt * 64);
;     };
;     auto loadBn = [&](bf16x8 (&rb)[4], int kt) {
; #pragma unroll
;         for (int i = 0; i < 4; ++i) rb[i] = *(const bf16x8*)(bpn + (size_t)(32 * i) * ldb + kt * 64);
;     };
;     auto store = [&](const typename AL::Raw& RA, const bf16x8 (&rb)[4], int kt, char* dA) {
;         bf16x8 ra[4];
;         al.cvt(RA, ra, AL::kmap(kt));
; #pragma unroll
;         for (int i = 0; i < 4; ++i) {
;             const int row = lrow + 32 * i;
;             const int off = row * 128 + ((lch ^ ((row >> 1) & 7)) << 4);
;             *(bf16x8*)(dA + off) = ra[i];
;             *(bf16x8*)(dA + 16384 + off) = rb[i];
;         }
;     };
;     auto compute = [&](const char* cA) {
;         const char* cB = cA + 16384;
;         bf16x8 a[2][2], b[2][2];
;         auto rd = [&](int set, int ks) {
; #pragma unroll
;             for (int mi = 0; mi < 2; ++mi) { const int row = wm * 64 + mi * 32 + r; a[set][mi] = *(const bf16x8*)(cA + row * 128 + (((2 * ks + h) ^ ((row >> 1) & 7)) << 4)); }
; #pragma unroll
;             for (int ni = 0; ni < 2; ++ni) { const int row = wn * 64 + ni * 32 + r; b[set][ni] = *(const bf16x8*)(cB + row * 128 + (((2 * ks + h) ^ ((row >> 1) & 7)) << 4)); }
;         };
;         auto mm = [&](int set) {
; #pragma unroll
;             for (int mi = 0; mi < 2; ++mi)
; #pragma unroll
;                 for (int ni = 0; ni < 2; ++ni) acc[mi][ni] = mfma32(a[set][mi], b[set][ni], acc[mi][ni]);
;         };
;         rd(0, 0); rd(1, 1);
;         __builtin_amdgcn_sched_barrier(0);
;         mm(0); rd(0, 2);
.LBB0_266:
	s_lshl_b32 s52, s95, 7
	s_lshl_b32 s16, s42, 7
	s_xor_b64 s[54:55], s[0:1], -1
	s_cmp_lg_u64 s[2:3], 0
	s_cselect_b32 s53, 0x80, 0
	s_lshl_b32 s26, s16, 11
	s_add_u32 s26, s26, s53
	s_add_u32 s2, s6, s26
	s_addc_u32 s3, s7, 0
	s_lshl_b32 s26, s52, 11
	s_add_u32 s26, s26, s53
	s_add_u32 s64, s8, s26
	s_addc_u32 s65, s9, 0
	v_lshrrev_b32_e32 v148, 6, v0
	v_and_b32_e32 v140, 63, v0
	v_readfirstlane_b32 s17, v148
	v_lshrrev_b32_e32 v141, 3, v140
	v_and_b32_e32 v142, 7, v140
	v_lshrrev_b32_e32 v143, 1, v141
	v_xor_b32_e32 v144, v142, v143
	v_xor_b32_e32 v145, 4, v144
	v_lshl_add_u32 v146, v148, 5, v141
	v_lshlrev_b32_e32 v147, 11, v146
	v_lshl_add_u32 v136, v144, 4, v147
	v_lshl_add_u32 v137, v145, 4, v147
	v_add_u32_e32 v137, 0x3c00, v137
	v_add_u32_e32 v138, 0x7800, v136
	v_add_u32_e32 v139, 0x7800, v137
	s_lshl_b32 s56, s17, 12
	s_add_i32 s57, s56, 0x4000
	s_add_i32 s58, s56, 0x8000
	s_add_i32 s59, s56, 0xc000
	s_cmp_lg_u32 s53, 0
	s_cbranch_scc1 .Lg1_pre
	s_mov_b32 m0, s56
	s_nop 0
	global_load_lds_dwordx4 v136, s[2:3]
	global_load_lds_dwordx4 v137, s[2:3] offset:1024
	global_load_lds_dwordx4 v138, s[2:3] offset:2048
	global_load_lds_dwordx4 v139, s[2:3] offset:3072
	s_add_u32 s2, s2, 0x80
	s_addc_u32 s3, s3, 0
	s_mov_b32 m0, s57
	s_nop 0
	global_load_lds_dwordx4 v136, s[64:65]
	global_load_lds_dwordx4 v137, s[64:65] offset:1024
	global_load_lds_dwordx4 v138, s[64:65] offset:2048
	global_load_lds_dwordx4 v139, s[64:65] offset:3072
	s_add_u32 s64, s64, 0x80
	s_addc_u32 s65, s65, 0
.Lg1_pre:
	v_bfe_u32 v152, v0, 5, 1
	v_lshlrev_b32_e32 v149, 6, v0
	v_and_b32_e32 v149, 0xffffe000, v149
	v_lshlrev_b32_e32 v150, 7, v0
	s_movk_i32 s26, 0xf80
	v_and_or_b32 v149, v150, s26, v149
	v_add_u32_e32 v168, 0, v149
	v_lshrrev_b32_e32 v149, 1, v0
	v_bitop3_b32 v149, v149, v152, 7 bitop3:0x6c
	v_bfe_u32 v151, v0, 1, 3
	v_lshlrev_b32_e32 v169, 4, v149
	v_and_b32_e32 v149, 0x2f80, v150
	v_add_u32_e32 v170, 0, v149
	v_bitop3_b32 v149, v152, v151, 2 bitop3:0x36
	v_lshlrev_b32_e32 v171, 4, v149
	v_bitop3_b32 v149, v152, v151, 4 bitop3:0x36
	v_lshlrev_b32_e32 v172, 4, v149
	v_bitop3_b32 v149, v152, v151, 6 bitop3:0x36
	v_lshlrev_b32_e32 v173, 4, v149
	v_mov_b32_e32 v2, 0
	v_mov_b32_e32 v3, v2
	v_mov_b32_e32 v4, v2
	v_mov_b32_e32 v5, v2
	v_mov_b32_e32 v6, v2
	v_mov_b32_e32 v7, v2
	v_mov_b32_e32 v8, v2
	v_mov_b32_e32 v9, v2
	v_mov_b32_e32 v10, v2
	v_mov_b32_e32 v11, v2
	v_mov_b32_e32 v12, v2
	v_mov_b32_e32 v13, v2
	v_mov_b32_e32 v14, v2
	v_mov_b32_e32 v15, v2
	v_mov_b32_e32 v16, v2
	v_mov_b32_e32 v17, v2
	v_mov_b32_e32 v18, v2
	v_mov_b32_e32 v19, v2
	v_mov_b32_e32 v20, v2
	v_mov_b32_e32 v21, v2
	v_mov_b32_e32 v22, v2
	v_mov_b32_e32 v23, v2
	v_mov_b32_e32 v24, v2
	v_mov_b32_e32 v25, v2
	v_mov_b32_e32 v26, v2
	v_mov_b32_e32 v27, v2
	v_mov_b32_e32 v28, v2
	v_mov_b32_e32 v29, v2
	v_mov_b32_e32 v30, v2
	v_mov_b32_e32 v31, v2
	v_mov_b32_e32 v32, v2
	v_mov_b32_e32 v33, v2
	v_mov_b32_e32 v34, v2
	v_mov_b32_e32 v35, v2
	v_mov_b32_e32 v36, v2
	v_mov_b32_e32 v37, v2
	v_mov_b32_e32 v38, v2
	v_mov_b32_e32 v39, v2
	v_mov_b32_e32 v40, v2
	v_mov_b32_e32 v41, v2
	v_mov_b32_e32 v42, v2
	v_mov_b32_e32 v43, v2
	v_mov_b32_e32 v44, v2
	v_mov_b32_e32 v45, v2
	v_mov_b32_e32 v46, v2
	v_mov_b32_e32 v47, v2
	v_mov_b32_e32 v48, v2
	v_mov_b32_e32 v49, v2
	v_mov_b32_e32 v50, v2
	v_mov_b32_e32 v51, v2
	v_mov_b32_e32 v52, v2
	v_mov_b32_e32 v53, v2
	v_mov_b32_e32 v54, v2
	v_mov_b32_e32 v55, v2
	v_mov_b32_e32 v56, v2
	v_mov_b32_e32 v57, v2
	v_mov_b32_e32 v58, v2
	v_mov_b32_e32 v59, v2
	v_mov_b32_e32 v60, v2
	v_mov_b32_e32 v61, v2
	v_mov_b32_e32 v62, v2
	v_mov_b32_e32 v63, v2
	v_mov_b32_e32 v64, v2
	v_mov_b32_e32 v65, v2
	s_mov_b32 s43, 0
	s_cmp_lg_u32 s53, 0
	s_cbranch_scc1 .Lg1_loop
	s_waitcnt vmcnt(0)
	s_barrier
; DI f32x16 mfma32(bf16x8 a, bf16x8 b, f32x16 c) { return __builtin_amdgcn_mfma_f32_32x32x16_bf16(a, b, c, 0, 0, 0); }
;     static DI int kmap(int kt) { return (kt >> 1) + 16 * (kt & 1); }
; template <class AL>
; DI void gemm_mainloop(f32x16 (&acc)[2][2], GemmRegs<AL>& G, bool pre, const AL& al, const u16* __restrict__ Bt, int ldb, int n0, int nk, char* sm,
;                       bool has_next, const AL& aln, int n0n) {
;     ...
;     auto compute = [&](const char* cA) {
;         const char* cB = cA + 16384;
;         bf16x8 a[2][2], b[2][2];
;         auto rd = [&](int set, int ks) {
; #pragma unroll
;             for (int mi = 0; mi < 2; ++mi) { const int row = wm * 64 + mi * 32 + r; a[set][mi] = *(const bf16x8*)(cA + row * 128 + (((2 * ks + h) ^ ((row >> 1) & 7)) << 4)); }
; #pragma unroll
;             for (int ni = 0; ni < 2; ++ni) { const int row = wn * 64 + ni * 32 + r; b[set][ni] = *(const bf16x8*)(cB + row * 128 + (((2 * ks + h) ^ ((row >> 1) & 7)) << 4)); }
;         };
;         auto mm = [&](int set) {
; #pragma unroll
;             for (int mi = 0; mi < 2; ++mi)
; #pragma unroll
;                 for (int ni = 0; ni < 2; ++ni) acc[mi][ni] = mfma32(a[set][mi], b[set][ni], acc[mi][ni]);
;         };
;         rd(0, 0); rd(1, 1);
;         __builtin_amdgcn_sched_barrier(0);
;         mm(0); rd(0, 2);
;         __builtin_amdgcn_sched_barrier(0);
;         mm(1); rd(1, 3);
;         __builtin_amdgcn_sched_barrier(0);
;         mm(0); mm(1);
;     };
;     ...
;     for (int kt = 0; kt < nk; kt += 2) {
;         compute(buf0);
;         store(RA1, RB1, kt + 1, buf1);
;         if (kt + 3 < nk) { al.load(RA1, AL::kmap(kt + 3)); loadB(RB1, AL::kmap(kt + 3)); }
;         else if (has_next) { aln.load(RA1, AL::kmap(1)); loadBn(RB1, AL::kmap(1)); }
;         __syncthreads();
;         compute(buf1);
;         if (kt + 2 < nk) {
;             store(RA0, RB0, kt + 2, buf0);
;             if (kt + 4 < nk) { al.load(RA0, AL::kmap(kt + 4)); loadB(RB0, AL::kmap(kt + 4)); }
;             else if (has_next) { aln.load(RA0, AL::kmap(0)); loadBn(RB0, AL::kmap(0)); }
;         }
;         __syncthreads();
;     }
.Lg1_loop:
	v_add_u32_e32 v174, v168, v169
	v_add_u32_e32 v175, v170, v169
	v_add_u32_e32 v176, v168, v171
	v_add_u32_e32 v177, v170, v171
	ds_read_b128 v[150:153], v174
	ds_read_b128 v[154:157], v174 offset:4096
	ds_read_b128 v[158:161], v175 offset:16384
	ds_read_b128 v[162:165], v175 offset:20480
	ds_read_b128 v[180:183], v176
	ds_read_b128 v[184:187], v176 offset:4096
	ds_read_b128 v[188:191], v177 offset:16384
	ds_read_b128 v[192:195], v177 offset:20480
	s_mov_b32 m0, s58
	s_nop 0
	global_load_lds_dwordx4 v136, s[2:3]
	global_load_lds_dwordx4 v137, s[2:3] offset:1024
	global_load_lds_dwordx4 v138, s[2:3] offset:2048
	global_load_lds_dwordx4 v139, s[2:3] offset:3072
	s_add_u32 s2, s2, 0x80
	s_addc_u32 s3, s3, 0
	s_waitcnt lgkmcnt(5)
	v_mfma_f32_32x32x16_bf16 v[50:65], v[150:153], v[158:161], v[50:65]
	v_add_u32_e32 v178, v168, v172
	v_add_u32_e32 v179, v170, v172
	s_waitcnt lgkmcnt(4)
	v_mfma_f32_32x32x16_bf16 v[34:49], v[150:153], v[162:165], v[34:49]
	v_mfma_f32_32x32x16_bf16 v[18:33], v[154:157], v[158:161], v[18:33]
	v_mfma_f32_32x32x16_bf16 v[2:17], v[154:157], v[162:165], v[2:17]
	ds_read_b128 v[150:153], v178
	ds_read_b128 v[154:157], v178 offset:4096
	ds_read_b128 v[158:161], v179 offset:16384
	ds_read_b128 v[162:165], v179 offset:20480
	s_mov_b32 m0, s59
	s_nop 0
	global_load_lds_dwordx4 v136, s[64:65]
	global_load_lds_dwordx4 v137, s[64:65] offset:1024
	global_load_lds_dwordx4 v138, s[64:65] offset:2048
	global_load_lds_dwordx4 v139, s[64:65] offset:3072
	s_add_u32 s64, s64, 0x80
	s_addc_u32 s65, s65, 0
	s_waitcnt lgkmcnt(5)
	v_mfma_f32_32x32x16_bf16 v[50:65], v[180:183], v[188:191], v[50:65]
	s_waitcnt lgkmcnt(4)
	v_mfma_f32_32x32x16_bf16 v[34:49], v[180:183], v[192:195], v[34:49]
	v_add_u32_e32 v180, v168, v173
	v_add_u32_e32 v181, v170, v173
	v_mfma_f32_32x32x16_bf16 v[18:33], v[184:187], v[188:191], v[18:33]
	v_mfma_f32_32x32x16_bf16 v[2:17], v[184:187], v[192:195], v[2:17]
	ds_read_b128 v[182:185], v180
	ds_read_b128 v[186:189], v180 offset:4096
	ds_read_b128 v[190:193], v181 offset:16384
	ds_read_b128 v[194:197], v181 offset:20480
	s_waitcnt lgkmcnt(5)
	v_mfma_f32_32x32x16_bf16 v[50:65], v[150:153], v[158:161], v[50:65]
	s_waitcnt lgkmcnt(4)
	v_mfma_f32_32x32x16_bf16 v[34:49], v[150:153], v[162:165], v[34:49]
	v_mfma_f32_32x32x16_bf16 v[18:33], v[154:157], v[158:161], v[18:33]
	v_mfma_f32_32x32x16_bf16 v[2:17], v[154:157], v[162:165], v[2:17]
	s_waitcnt lgkmcnt(1)
	v_mfma_f32_32x32x16_bf16 v[50:65], v[182:185], v[190:193], v[50:65]
	s_waitcnt lgkmcnt(0)
	v_mfma_f32_32x32x16_bf16 v[34:49], v[182:185], v[194:197], v[34:49]
	v_mfma_f32_32x32x16_bf16 v[18:33], v[186:189], v[190:193], v[18:33]
	v_mfma_f32_32x32x16_bf16 v[2:17], v[186:189], v[194:197], v[2:17]
	s_waitcnt vmcnt(0)
	s_barrier
	s_mov_b32 s53, 1
	s_cmp_lt_u32 s43, 14
	s_cbranch_scc1 .Lg1_bgo
	s_mov_b32 s53, 0
	s_and_b64 vcc, exec, s[0:1]
	s_cbranch_vccz .Lg1_bgo
	s_mov_b32 s53, 1
	s_lshl_b32 s26, s94, 18
	s_add_u32 s2, s6, s26
	s_addc_u32 s3, s7, 0
	s_lshl_b32 s26, s93, 18
	s_add_u32 s64, s8, s26
	s_addc_u32 s65, s9, 0
.Lg1_bgo:
	ds_read_b128 v[150:153], v174 offset:32768
	ds_read_b128 v[154:157], v174 offset:36864
	ds_read_b128 v[158:161], v175 offset:49152
	ds_read_b128 v[162:165], v175 offset:53248
	ds_read_b128 v[182:185], v176 offset:32768
	ds_read_b128 v[186:189], v176 offset:36864
	ds_read_b128 v[190:193], v177 offset:49152
	ds_read_b128 v[174:177], v177 offset:53248
	s_cmp_eq_u32 s53, 0
	s_cbranch_scc1 .Lg1_skipA
	s_mov_b32 m0, s56
	s_nop 0
	global_load_lds_dwordx4 v136, s[2:3]
	global_load_lds_dwordx4 v137, s[2:3] offset:1024
	global_load_lds_dwordx4 v138, s[2:3] offset:2048
	global_load_lds_dwordx4 v139, s[2:3] offset:3072
	s_add_u32 s2, s2, 0x80
	s_addc_u32 s3, s3, 0
.Lg1_skipA:
	s_waitcnt lgkmcnt(5)
	v_mfma_f32_32x32x16_bf16 v[50:65], v[150:153], v[158:161], v[50:65]
	s_waitcnt lgkmcnt(4)
	v_mfma_f32_32x32x16_bf16 v[34:49], v[150:153], v[162:165], v[34:49]
	v_mfma_f32_32x32x16_bf16 v[18:33], v[154:157], v[158:161], v[18:33]
	v_mfma_f32_32x32x16_bf16 v[2:17], v[154:157], v[162:165], v[2:17]
	ds_read_b128 v[150:153], v178 offset:32768
	ds_read_b128 v[154:157], v178 offset:36864
	ds_read_b128 v[158:161], v179 offset:49152
	ds_read_b128 v[162:165], v179 offset:53248
	s_cmp_eq_u32 s53, 0
	s_cbranch_scc1 .Lg1_skipB
	s_mov_b32 m0, s57
	s_nop 0
	global_load_lds_dwordx4 v136, s[64:65]
	global_load_lds_dwordx4 v137, s[64:65] offset:1024
	global_load_lds_dwordx4 v138, s[64:65] offset:2048
	global_load_lds_dwordx4 v139, s[64:65] offset:3072
	s_add_u32 s64, s64, 0x80
	s_addc_u32 s65, s65, 0
.Lg1_skipB:
	s_waitcnt lgkmcnt(5)
	v_mfma_f32_32x32x16_bf16 v[50:65], v[182:185], v[190:193], v[50:65]
	s_waitcnt lgkmcnt(4)
	v_mfma_f32_32x32x16_bf16 v[34:49], v[182:185], v[174:177], v[34:49]
	v_mfma_f32_32x32x16_bf16 v[18:33], v[186:189], v[190:193], v[18:33]
	v_mfma_f32_32x32x16_bf16 v[2:17], v[186:189], v[174:177], v[2:17]
	ds_read_b128 v[174:177], v180 offset:32768
	ds_read_b128 v[182:185], v180 offset:36864
	ds_read_b128 v[186:189], v181 offset:49152
	ds_read_b128 v[178:181], v181 offset:53248
	s_waitcnt lgkmcnt(5)
	v_mfma_f32_32x32x16_bf16 v[50:65], v[150:153], v[158:161], v[50:65]
	s_waitcnt lgkmcnt(4)
	v_mfma_f32_32x32x16_bf16 v[34:49], v[150:153], v[162:165], v[34:49]
	v_mfma_f32_32x32x16_bf16 v[18:33], v[154:157], v[158:161], v[18:33]
	v_mfma_f32_32x32x16_bf16 v[2:17], v[154:157], v[162:165], v[2:17]
	s_waitcnt lgkmcnt(1)
	v_mfma_f32_32x32x16_bf16 v[50:65], v[174:177], v[186:189], v[50:65]
	s_waitcnt lgkmcnt(0)
	v_mfma_f32_32x32x16_bf16 v[34:49], v[174:177], v[178:181], v[34:49]
	v_mfma_f32_32x32x16_bf16 v[18:33], v[182:185], v[186:189], v[18:33]
	v_mfma_f32_32x32x16_bf16 v[2:17], v[182:185], v[178:181], v[2:17]
	s_waitcnt vmcnt(0)
	s_barrier
	s_add_i32 s43, s43, 2
	s_cmp_lt_u32 s43, 16
	s_cbranch_scc1 .Lg1_loop
